# ret_out: s_prev and k tiles of each item staged through LDS (coalesced fill loads + ds_read fragments) instead of row-per-lane global fragment loads
# speedup vs baseline: 1.0141x; 1.0102x over previous
.LBB0_913:
	s_or_b64 exec, exec, s[0:1]
	v_readlane_b32 s20, v253, 13
	v_readlane_b32 s21, v253, 14
	v_ashrrev_i32_e32 v201, 31, v10
	v_mov_b32_e32 v200, v10
	v_lshlrev_b64 v[200:201], 15, v[200:201]
	v_lshlrev_b32_e32 v202, 4, v172
	v_mov_b32_e32 v203, 0
	v_lshl_add_u64 v[200:201], s[20:21], 0, v[200:201]
	v_lshl_add_u64 v[232:233], v[200:201], 0, v[202:203]
	s_mov_b64 s[20:21], 0x1000
	global_load_dwordx4 v[200:203], v[232:233], off
	v_lshl_add_u64 v[232:233], v[232:233], 0, s[20:21]
	global_load_dwordx4 v[204:207], v[232:233], off
	v_lshl_add_u64 v[232:233], v[232:233], 0, s[20:21]
	global_load_dwordx4 v[208:211], v[232:233], off
	v_lshl_add_u64 v[232:233], v[232:233], 0, s[20:21]
	global_load_dwordx4 v[212:215], v[232:233], off
	v_lshl_add_u64 v[232:233], v[232:233], 0, s[20:21]
	global_load_dwordx4 v[216:219], v[232:233], off
	v_lshl_add_u64 v[232:233], v[232:233], 0, s[20:21]
	global_load_dwordx4 v[220:223], v[232:233], off
	v_lshl_add_u64 v[232:233], v[232:233], 0, s[20:21]
	global_load_dwordx4 v[224:227], v[232:233], off
	v_lshl_add_u64 v[232:233], v[232:233], 0, s[20:21]
	global_load_dwordx4 v[228:231], v[232:233], off
	v_and_b32_e32 v169, 3, v2
	v_cvt_f32_ubyte0_e32 v0, v169
	v_sub_f32_e32 v0, 0xc0a00000, v0
	v_cmp_gt_f32_e32 vcc, s34, v0
	s_mov_b32 s0, 0x3f2aaaab
	v_and_b32_e32 v113, 31, v172
	v_cndmask_b32_e32 v2, 0, v187, vcc
	v_add_f32_e32 v0, v0, v2
	v_exp_f32_e32 v0, v0
	v_cndmask_b32_e32 v2, 0, v188, vcc
	v_ashrrev_i32_e32 v191, 1, v172
	v_and_or_b32 v193, v191, 32, v113
	v_ldexp_f32 v11, v0, v2
	v_sub_f32_e32 v0, 1.0, v11
	v_add_f32_e32 v2, -1.0, v0
	v_sub_f32_e32 v3, v2, v0
	v_add_f32_e32 v3, 1.0, v3
	v_sub_f32_e64 v2, -v11, v2
	v_add_f32_e32 v4, v2, v3
	v_frexp_mant_f32_e32 v5, v0
	v_cvt_f64_f32_e32 v[2:3], v0
	v_frexp_exp_i32_f64_e32 v2, v[2:3]
	v_cmp_gt_f32_e32 vcc, s0, v5
	v_readlane_b32 s0, v252, 55
	v_readlane_b32 s1, v252, 56
	v_subbrev_co_u32_e32 v111, vcc, 0, v2, vcc
	v_sub_u32_e32 v2, 0, v111
	v_ldexp_f32 v0, v0, v2
	v_ldexp_f32 v2, v4, v2
	v_add_f32_e32 v4, -1.0, v0
	v_add_f32_e32 v3, 1.0, v4
	v_sub_f32_e32 v3, v0, v3
	v_add_f32_e32 v5, v2, v3
	v_add_f32_e32 v3, 1.0, v0
	v_add_f32_e32 v6, -1.0, v3
	v_sub_f32_e32 v0, v0, v6
	v_add_f32_e32 v0, v2, v0
	v_add_f32_e32 v114, v3, v0
	v_rcp_f32_e32 v116, v114
	v_sub_f32_e32 v2, v114, v3
	v_add_f32_e32 v3, v4, v5
	v_sub_f32_e32 v115, v0, v2
	v_mul_f32_e32 v117, v3, v116
	v_mul_f32_e32 v18, v114, v117
	v_sub_f32_e32 v0, v3, v4
	v_fma_f32 v4, v117, v114, -v18
	v_fmac_f32_e32 v4, v117, v115
	v_add_f32_e32 v2, v18, v4
	v_sub_f32_e32 v19, v3, v2
	v_sub_f32_e32 v0, v5, v0
	v_pk_add_f32 v[6:7], v[2:3], v[18:19] neg_lo:[0,1] neg_hi:[0,1]
	v_mov_b32_e32 v5, v2
	v_pk_add_f32 v[2:3], v[6:7], v[4:5] neg_lo:[0,1] neg_hi:[0,1]
	v_bfe_u32 v173, v172, 5, 1
	v_add_f32_e32 v0, v0, v3
	v_add_f32_e32 v18, v2, v0
	v_add_u32_e32 v2, v112, v193
	v_ashrrev_i32_e32 v3, 31, v2
	v_lshlrev_b64 v[174:175], 10, v[2:3]
	v_lshl_add_u64 v[2:3], s[0:1], 0, v[174:175]
	v_lshlrev_b32_e32 v0, 8, v169
	v_lshl_add_u64 v[2:3], v[2:3], 0, v[0:1]
	v_lshlrev_b32_e32 v32, 4, v173
	v_mov_b32_e32 v33, v1
	v_lshl_add_u64 v[2:3], v[2:3], 0, v[32:33]
	global_load_dwordx4 v[78:81], v[2:3], off
	global_load_dwordx4 v[74:77], v[2:3], off offset:32
	global_load_dwordx4 v[70:73], v[2:3], off offset:64
	global_load_dwordx4 v[66:69], v[2:3], off offset:96
	global_load_dwordx4 v[62:65], v[2:3], off offset:128
	global_load_dwordx4 v[58:61], v[2:3], off offset:160
	global_load_dwordx4 v[54:57], v[2:3], off offset:192
	global_load_dwordx4 v[50:53], v[2:3], off offset:224
	v_add_u32_e32 v2, v112, v113
	v_ashrrev_i32_e32 v3, 31, v2
	v_readlane_b32 s20, v252, 53
	v_lshlrev_b64 v[2:3], 10, v[2:3]
	v_readlane_b32 s21, v252, 54
	v_and_b32_e32 v192, 0xffffffc0, v191
	v_lshlrev_b32_e32 v16, 1, v16
	v_mov_b32_e32 v17, v1
	v_lshlrev_b32_e32 v20, 3, v173
	v_mov_b32_e32 v21, v1
	v_lshl_add_u64 v[2:3], s[20:21], 0, v[2:3]
	v_or_b32_e32 v110, v192, v113
	v_lshl_add_u64 v[12:13], v[12:13], 0, v[16:17]
	v_lshl_add_u64 v[2:3], v[2:3], 0, v[0:1]
	v_lshl_add_u64 v[12:13], v[12:13], 0, v[20:21]
	v_mad_i64_i32 v[16:17], s[0:1], v14, v110, 0
	v_lshl_add_u64 v[22:23], v[2:3], 0, v[32:33]
	v_lshl_add_u64 v[16:17], v[16:17], 1, v[12:13]
	v_lshrrev_b32_e32 v232, 4, v172
	v_add_u32_e32 v232, v112, v232
	v_ashrrev_i32_e32 v233, 31, v232
	v_lshlrev_b64 v[232:233], 10, v[232:233]
	v_and_b32_e32 v254, 15, v172
	v_lshlrev_b32_e32 v254, 4, v254
	v_mov_b32_e32 v255, 0
	v_lshl_add_u64 v[232:233], s[20:21], 0, v[232:233]
	v_lshl_add_u64 v[232:233], v[232:233], 0, v[0:1]
	v_lshl_add_u64 v[232:233], v[232:233], 0, v[254:255]
	s_mov_b64 s[20:21], 0x4000
	global_load_dwordx4 v[46:49], v[232:233], off
	v_lshl_add_u64 v[232:233], v[232:233], 0, s[20:21]
	global_load_dwordx4 v[42:45], v[232:233], off
	v_lshl_add_u64 v[232:233], v[232:233], 0, s[20:21]
	global_load_dwordx4 v[38:41], v[232:233], off
	v_lshl_add_u64 v[232:233], v[232:233], 0, s[20:21]
	global_load_dwordx4 v[28:31], v[232:233], off
	global_load_dwordx2 v[34:35], v[16:17], off
	global_load_dwordx2 v[36:37], v[16:17], off offset:16
	global_load_dwordx2 v[106:107], v[16:17], off offset:32
	global_load_dwordx2 v[108:109], v[16:17], off offset:48
	global_load_dwordx2 v[102:103], v[16:17], off offset:64
	global_load_dwordx2 v[104:105], v[16:17], off offset:80
	global_load_dwordx2 v[98:99], v[16:17], off offset:96
	global_load_dwordx2 v[100:101], v[16:17], off offset:112
	v_or_b32_e32 v16, 32, v110
	v_mad_i64_i32 v[16:17], s[0:1], v14, v16, 0
	v_lshl_add_u64 v[12:13], v[16:17], 1, v[12:13]
	global_load_dwordx2 v[94:95], v[12:13], off
	global_load_dwordx2 v[96:97], v[12:13], off offset:16
	global_load_dwordx2 v[90:91], v[12:13], off offset:32
	global_load_dwordx2 v[92:93], v[12:13], off offset:48
	global_load_dwordx2 v[86:87], v[12:13], off offset:64
	global_load_dwordx2 v[88:89], v[12:13], off offset:80
	global_load_dwordx2 v[82:83], v[12:13], off offset:96
	global_load_dwordx2 v[84:85], v[12:13], off offset:112
	v_add_f32_e32 v15, v19, v18
	v_mul_f32_e32 v118, v116, v15
	v_mul_f32_e32 v12, v114, v118
	v_fma_f32 v16, v118, v114, -v12
	v_fmac_f32_e32 v16, v118, v115
	v_sub_f32_e32 v13, v19, v15
	v_add_f32_e32 v14, v12, v16
	v_add_f32_e32 v20, v18, v13
	v_sub_f32_e32 v13, v15, v14
	v_pk_add_f32 v[18:19], v[14:15], v[12:13] neg_lo:[0,1] neg_hi:[0,1]
	v_mov_b32_e32 v17, v14
	v_pk_add_f32 v[14:15], v[18:19], v[16:17] neg_lo:[0,1] neg_hi:[0,1]
	s_mov_b32 s0, 0x3f317218
	v_add_f32_e32 v12, v20, v15
	v_add_f32_e32 v12, v14, v12
	v_add_f32_e32 v12, v13, v12
	v_add_f32_e32 v13, v117, v118
	v_sub_f32_e32 v14, v13, v117
	v_mul_f32_e32 v12, v116, v12
	v_sub_f32_e32 v14, v118, v14
	v_add_f32_e32 v14, v14, v12
	v_add_f32_e32 v16, v13, v14
	v_mul_f32_e32 v17, v16, v16
	v_fmamk_f32 v12, v17, 0x3e9b6dac, v185
	v_fmaak_f32 v171, v17, v12, 0x3f2aaada
	v_cvt_f32_i32_e32 v12, v111
	v_sub_f32_e32 v13, v16, v13
	v_sub_f32_e32 v13, v14, v13
	v_ldexp_f32 v18, v13, 1
	v_mul_f32_e32 v13, v16, v17
	v_ldexp_f32 v15, v16, 1
	v_pk_mul_f32 v[16:17], v[12:13], v[170:171]
	v_cmp_nlt_f32_e32 vcc, 1.0, v11
	v_fma_f32 v14, v12, s0, -v16
	v_fmac_f32_e32 v14, 0xb102e308, v12
	v_pk_add_f32 v[12:13], v[16:17], v[14:15]
	s_mov_b32 s0, 0x33800000
	v_sub_f32_e32 v15, v13, v15
	v_sub_f32_e32 v15, v17, v15
	v_add_f32_e32 v19, v18, v15
	v_mov_b32_e32 v18, v16
	v_pk_add_f32 v[16:17], v[12:13], v[16:17] neg_lo:[0,1] neg_hi:[0,1]
	v_pk_add_f32 v[20:21], v[12:13], v[18:19]
	v_mov_b32_e32 v15, v12
	v_mov_b32_e32 v17, v21
	v_pk_add_f32 v[22:23], v[14:15], v[16:17] neg_lo:[0,1] neg_hi:[0,1]
	v_pk_add_f32 v[14:15], v[14:15], v[16:17]
	v_mov_b32_e32 v18, v19
	v_pk_add_f32 v[16:17], v[14:15], v[12:13] op_sel:[1,0] op_sel_hi:[0,1] neg_lo:[0,1] neg_hi:[0,1]
	v_pk_add_f32 v[114:115], v[20:21], v[16:17] op_sel_hi:[1,0] neg_lo:[0,1] neg_hi:[0,1]
	v_mov_b32_e32 v20, v21
	v_mov_b32_e32 v21, v15
	v_pk_mov_b32 v[16:17], v[12:13], v[16:17] op_sel:[1,0]
	v_mov_b32_e32 v19, v12
	v_pk_add_f32 v[16:17], v[20:21], v[16:17] neg_lo:[0,1] neg_hi:[0,1]
	v_mov_b32_e32 v114, v22
	v_pk_add_f32 v[12:13], v[18:19], v[16:17] neg_lo:[0,1] neg_hi:[0,1]
	v_mov_b32_e32 v23, v15
	v_pk_add_f32 v[16:17], v[114:115], v[12:13]
	v_lshlrev_b32_e32 v171, 2, v173
	v_pk_add_f32 v[18:19], v[16:17], v[16:17] op_sel:[0,1] op_sel_hi:[1,0]
	v_ashrrev_i32_e32 v111, 31, v110
	v_pk_add_f32 v[14:15], v[14:15], v[18:19] op_sel:[1,0] op_sel_hi:[0,1]
	v_mov_b32_e32 v17, v14
	v_pk_add_f32 v[20:21], v[16:17], v[22:23] neg_lo:[0,1] neg_hi:[0,1]
	v_mov_b32_e32 v13, v18
	v_sub_f32_e32 v15, v16, v20
	v_pk_add_f32 v[12:13], v[12:13], v[20:21] neg_lo:[0,1] neg_hi:[0,1]
	v_sub_f32_e32 v15, v22, v15
	v_add_f32_e32 v12, v12, v15
	v_add_f32_e32 v12, v12, v13
	v_add_f32_e32 v12, v14, v12
	v_cndmask_b32_e32 v12, v189, v12, vcc
	v_cmp_neq_f32_e32 vcc, 1.0, v11
	s_nop 1
	v_cndmask_b32_e32 v12, v190, v12, vcc
	v_cmp_gt_f32_e32 vcc, s0, v11
	v_readlane_b32 s0, v253, 13
	v_readlane_b32 s1, v253, 14
	v_cndmask_b32_e64 v11, v12, -v11, vcc
	v_mul_f32_e32 v194, 0x3fb8aa3b, v11
	v_ashrrev_i32_e32 v11, 31, v10
	v_lshlrev_b64 v[10:11], 15, v[10:11]
	v_lshl_add_u64 v[154:155], s[0:1], 0, v[10:11]
	s_waitcnt vmcnt(16)
	v_lshrrev_b32_e32 v232, 4, v172
	v_and_b32_e32 v233, 15, v172
	v_mul_u32_u24_e32 v232, 0x110, v232
	v_lshl_add_u32 v232, v233, 4, v232
	v_add_u32_e32 v232, v232, v182
	v_mul_u32_u24_e32 v241, 0x110, v113
	v_add3_u32 v241, v241, v32, v182
	v_add_u32_e32 v232, 0x9000, v232
	v_add_u32_e32 v241, 0x9000, v241
	ds_write_b128 v232, v[46:49]
	ds_write_b128 v232, v[42:45] offset:4352
	ds_write_b128 v232, v[38:41] offset:8704
	ds_write_b128 v232, v[28:31] offset:13056
	s_waitcnt lgkmcnt(0)
	s_barrier
	ds_read_b128 v[6:9], v241
	ds_read_b128 v[46:49], v241 offset:32
	ds_read_b128 v[42:45], v241 offset:64
	ds_read_b128 v[38:41], v241 offset:96
	ds_read_b128 v[28:31], v241 offset:128
	ds_read_b128 v[2:5], v241 offset:160
	ds_read_b128 v[24:27], v241 offset:192
	ds_read_b128 v[150:153], v241 offset:224
	s_waitcnt lgkmcnt(0)
	v_mfma_f32_32x32x16_bf16 v[8:23], v[6:9], v[78:81], 0
	v_or_b32_e32 v195, 32, v113
	v_lshlrev_b64 v[6:7], 8, v[110:111]
	v_lshl_add_u64 v[6:7], v[154:155], 0, v[6:7]
	v_lshl_add_u64 v[6:7], v[6:7], 0, v[32:33]
	s_nop 0
	v_mfma_f32_32x32x16_bf16 v[8:23], v[46:49], v[74:77], v[8:23]
	s_nop 0
	v_mfma_f32_32x32x16_bf16 v[8:23], v[42:45], v[70:73], v[8:23]
	s_nop 0
	v_mfma_f32_32x32x16_bf16 v[8:23], v[38:41], v[66:69], v[8:23]
	s_nop 0
	v_mfma_f32_32x32x16_bf16 v[8:23], v[28:31], v[62:65], v[8:23]
	v_add_u32_e32 v28, v112, v195
	v_ashrrev_i32_e32 v29, 31, v28
	v_lshlrev_b64 v[28:29], 10, v[28:29]
	v_lshl_add_u64 v[28:29], s[20:21], 0, v[28:29]
	v_lshl_add_u64 v[28:29], v[28:29], 0, v[0:1]
	v_lshl_add_u64 v[28:29], v[28:29], 0, v[32:33]
	s_nop 0
	v_mfma_f32_32x32x16_bf16 v[8:23], v[2:5], v[58:61], v[8:23]
	ds_read_b128 v[2:5], v241 offset:8704
	ds_read_b128 v[146:149], v241 offset:8736
	ds_read_b128 v[142:145], v241 offset:8768
	ds_read_b128 v[138:141], v241 offset:8800
	ds_read_b128 v[130:133], v241 offset:8832
	ds_read_b128 v[126:129], v241 offset:8864
	ds_read_b128 v[134:137], v241 offset:8896
	s_nop 0
	ds_read_b128 v[28:31], v241 offset:8928
	s_nop 0
	v_mfma_f32_32x32x16_bf16 v[8:23], v[24:27], v[54:57], v[8:23]
	s_waitcnt vmcnt(16)
	v_lshrrev_b32_e32 v232, 4, v172
	v_and_b32_e32 v233, 15, v172
	v_mul_u32_u24_e32 v232, 0x110, v232
	v_lshl_add_u32 v232, v233, 4, v232
	v_add_u32_e32 v232, v232, v182
	v_mul_u32_u24_e32 v233, 0x110, v110
	v_add3_u32 v233, v233, v32, v182
	v_add_u32_e32 v232, 0x800, v232
	v_add_u32_e32 v233, 0x800, v233
	ds_write_b128 v232, v[200:203]
	ds_write_b128 v232, v[204:207] offset:4352
	ds_write_b128 v232, v[208:211] offset:8704
	ds_write_b128 v232, v[212:215] offset:13056
	ds_write_b128 v232, v[216:219] offset:17408
	ds_write_b128 v232, v[220:223] offset:21760
	ds_write_b128 v232, v[224:227] offset:26112
	ds_write_b128 v232, v[228:231] offset:30464
	s_waitcnt lgkmcnt(0)
	s_barrier
	ds_read_b128 v[24:27], v233
	ds_read_b128 v[122:125], v233 offset:32
	ds_read_b128 v[118:121], v233 offset:64
	ds_read_b128 v[114:117], v233 offset:96
	ds_read_b128 v[110:113], v233 offset:128
	ds_read_b128 v[46:49], v233 offset:160
	ds_read_b128 v[42:45], v233 offset:192
	ds_read_b128 v[38:41], v233 offset:224
	s_nop 0
	v_mfma_f32_32x32x16_bf16 v[8:23], v[150:153], v[50:53], v[8:23]
	v_min_u32_e32 v0, v171, v193
	v_max_u32_e32 v6, v171, v193
	v_sub_u32_e32 v0, v6, v0
	v_cvt_f32_u32_e32 v0, v0
	v_or_b32_e32 v6, 1, v171
	v_mul_f32_e32 v7, v194, v0
	v_cmp_gt_f32_e32 vcc, s34, v7
	s_nop 1
	v_cndmask_b32_e32 v7, 0, v187, vcc
	v_fmac_f32_e32 v7, v194, v0
	v_exp_f32_e32 v0, v7
	v_min_u32_e32 v7, v6, v193
	v_max_u32_e32 v6, v6, v193
	v_sub_u32_e32 v6, v6, v7
	v_cvt_f32_u32_e32 v7, v6
	v_cndmask_b32_e32 v6, 0, v188, vcc
	v_ldexp_f32 v6, v0, v6
	v_mul_f32_e32 v0, v194, v7
	v_cmp_gt_f32_e32 vcc, s34, v0
	s_nop 1
	v_cndmask_b32_e32 v0, 0, v187, vcc
	v_fmac_f32_e32 v0, v194, v7
	v_exp_f32_e32 v0, v0
	v_or_b32_e32 v7, 2, v171
	v_min_u32_e32 v150, v7, v193
	v_max_u32_e32 v7, v7, v193
	v_sub_u32_e32 v7, v7, v150
	v_cvt_f32_u32_e32 v152, v7
	v_cndmask_b32_e32 v7, 0, v188, vcc
	v_ldexp_f32 v7, v0, v7
	v_pk_mul_f32 v[150:151], v[8:9], v[6:7]
	v_or_b32_e32 v6, 3, v171
	v_min_u32_e32 v7, v6, v193
	v_max_u32_e32 v6, v6, v193
	v_sub_u32_e32 v6, v6, v7
	v_cvt_f32_u32_e32 v6, v6
	v_mul_f32_e32 v0, v194, v152
	v_cmp_gt_f32_e32 vcc, s34, v0
	v_mul_f32_e32 v8, v194, v6
	s_nop 0
	v_cndmask_b32_e32 v0, 0, v187, vcc
	v_cndmask_b32_e32 v7, 0, v188, vcc
	v_cmp_gt_f32_e32 vcc, s34, v8
	v_fmac_f32_e32 v0, v194, v152
	v_exp_f32_e32 v0, v0
	v_cndmask_b32_e32 v8, 0, v187, vcc
	v_fmac_f32_e32 v8, v194, v6
	v_or_b32_e32 v6, 8, v171
	v_min_u32_e32 v9, v6, v193
	v_max_u32_e32 v6, v6, v193
	v_sub_u32_e32 v6, v6, v9
	v_exp_f32_e32 v8, v8
	v_cvt_f32_u32_e32 v9, v6
	v_ldexp_f32 v6, v0, v7
	v_cndmask_b32_e32 v0, 0, v188, vcc
	v_ldexp_f32 v7, v8, v0
	v_mul_f32_e32 v0, v194, v9
	v_cmp_gt_f32_e32 vcc, s34, v0
	v_or_b32_e32 v8, 9, v171
	v_pk_mul_f32 v[152:153], v[10:11], v[6:7]
	v_cndmask_b32_e32 v0, 0, v187, vcc
	v_fmac_f32_e32 v0, v194, v9
	v_min_u32_e32 v9, v8, v193
	v_max_u32_e32 v8, v8, v193
	v_sub_u32_e32 v8, v8, v9
	v_exp_f32_e32 v0, v0
	v_cvt_f32_u32_e32 v8, v8
	v_cndmask_b32_e32 v6, 0, v188, vcc
	v_or_b32_e32 v7, 10, v171
	v_ldexp_f32 v6, v0, v6
	v_mul_f32_e32 v0, v194, v8
	v_cmp_gt_f32_e32 vcc, s34, v0
	s_nop 1
	v_cndmask_b32_e32 v0, 0, v187, vcc
	v_fmac_f32_e32 v0, v194, v8
	v_exp_f32_e32 v0, v0
	v_min_u32_e32 v8, v7, v193
	v_max_u32_e32 v7, v7, v193
	v_sub_u32_e32 v7, v7, v8
	v_cvt_f32_u32_e32 v8, v7
	v_cndmask_b32_e32 v7, 0, v188, vcc
	v_ldexp_f32 v7, v0, v7
	v_pk_mul_f32 v[156:157], v[12:13], v[6:7]
	v_or_b32_e32 v6, 11, v171
	v_min_u32_e32 v7, v6, v193
	v_max_u32_e32 v6, v6, v193
	v_sub_u32_e32 v6, v6, v7
	v_cvt_f32_u32_e32 v6, v6
	v_mul_f32_e32 v0, v194, v8
	v_cmp_gt_f32_e32 vcc, s34, v0
	s_nop 1
	v_cndmask_b32_e32 v0, 0, v187, vcc
	v_fmac_f32_e32 v0, v194, v8
	v_mul_f32_e32 v8, v194, v6
	v_cndmask_b32_e32 v7, 0, v188, vcc
	v_cmp_gt_f32_e32 vcc, s34, v8
	v_exp_f32_e32 v0, v0
	s_nop 0
	v_cndmask_b32_e32 v8, 0, v187, vcc
	v_fmac_f32_e32 v8, v194, v6
	v_or_b32_e32 v6, 16, v171
	v_min_u32_e32 v9, v6, v193
	v_max_u32_e32 v6, v6, v193
	v_sub_u32_e32 v6, v6, v9
	v_exp_f32_e32 v8, v8
	v_cvt_f32_u32_e32 v9, v6
	v_ldexp_f32 v6, v0, v7
	v_cndmask_b32_e32 v0, 0, v188, vcc
	v_ldexp_f32 v7, v8, v0
	v_mul_f32_e32 v0, v194, v9
	v_cmp_gt_f32_e32 vcc, s34, v0
	v_or_b32_e32 v8, 17, v171
	v_pk_mul_f32 v[158:159], v[14:15], v[6:7]
	v_cndmask_b32_e32 v0, 0, v187, vcc
	v_fmac_f32_e32 v0, v194, v9
	v_min_u32_e32 v9, v8, v193
	v_max_u32_e32 v8, v8, v193
	v_sub_u32_e32 v8, v8, v9
	v_exp_f32_e32 v0, v0
	v_cvt_f32_u32_e32 v8, v8
	v_cndmask_b32_e32 v6, 0, v188, vcc
	v_or_b32_e32 v7, 18, v171
	v_ldexp_f32 v6, v0, v6
	v_mul_f32_e32 v0, v194, v8
	v_cmp_gt_f32_e32 vcc, s34, v0
	s_nop 1
	v_cndmask_b32_e32 v0, 0, v187, vcc
	v_fmac_f32_e32 v0, v194, v8
	v_exp_f32_e32 v0, v0
	v_min_u32_e32 v8, v7, v193
	v_max_u32_e32 v7, v7, v193
	v_sub_u32_e32 v7, v7, v8
	v_cvt_f32_u32_e32 v8, v7
	v_cndmask_b32_e32 v7, 0, v188, vcc
	v_ldexp_f32 v7, v0, v7
	v_pk_mul_f32 v[160:161], v[16:17], v[6:7]
	v_or_b32_e32 v6, 19, v171
	v_min_u32_e32 v7, v6, v193
	v_max_u32_e32 v6, v6, v193
	v_sub_u32_e32 v6, v6, v7
	v_cvt_f32_u32_e32 v6, v6
	v_mul_f32_e32 v0, v194, v8
	v_cmp_gt_f32_e32 vcc, s34, v0
	s_nop 1
	v_cndmask_b32_e32 v0, 0, v187, vcc
	v_fmac_f32_e32 v0, v194, v8
	v_mul_f32_e32 v8, v194, v6
	v_cndmask_b32_e32 v7, 0, v188, vcc
	v_cmp_gt_f32_e32 vcc, s34, v8
	v_exp_f32_e32 v0, v0
	s_nop 0
	v_cndmask_b32_e32 v8, 0, v187, vcc
	v_fmac_f32_e32 v8, v194, v6
	v_exp_f32_e32 v6, v8
	v_or_b32_e32 v8, 24, v171
	v_min_u32_e32 v9, v8, v193
	v_max_u32_e32 v8, v8, v193
	v_sub_u32_e32 v8, v8, v9
	v_cvt_f32_u32_e32 v8, v8
	v_ldexp_f32 v176, v0, v7
	v_cndmask_b32_e32 v0, 0, v188, vcc
	v_ldexp_f32 v177, v6, v0
	v_mul_f32_e32 v0, v194, v8
	v_cmp_gt_f32_e32 vcc, s34, v0
	v_or_b32_e32 v6, 25, v171
	v_min_u32_e32 v7, v6, v193
	v_cndmask_b32_e32 v0, 0, v187, vcc
	v_max_u32_e32 v6, v6, v193
	v_fmac_f32_e32 v0, v194, v8
	v_sub_u32_e32 v178, v6, v7
	s_nop 0
	v_mfma_f32_32x32x16_bf16 v[2:17], v[2:5], v[78:81], 0
	v_exp_f32_e32 v0, v0
	v_cvt_f32_u32_e32 v178, v178
	v_pk_mul_f32 v[18:19], v[18:19], v[176:177]
	v_cndmask_b32_e32 v176, 0, v188, vcc
	v_ldexp_f32 v176, v0, v176
	v_mul_f32_e32 v0, v194, v178
	v_cmp_gt_f32_e32 vcc, s34, v0
	s_nop 0
	v_mfma_f32_32x32x16_bf16 v[2:17], v[146:149], v[74:77], v[2:17]
	v_or_b32_e32 v146, 26, v171
	v_cndmask_b32_e32 v0, 0, v187, vcc
	v_fmac_f32_e32 v0, v194, v178
	v_exp_f32_e32 v0, v0
	v_min_u32_e32 v147, v146, v193
	v_max_u32_e32 v146, v146, v193
	v_sub_u32_e32 v146, v146, v147
	s_nop 0
	v_mfma_f32_32x32x16_bf16 v[2:17], v[142:145], v[70:73], v[2:17]
	v_cndmask_b32_e32 v142, 0, v188, vcc
	v_ldexp_f32 v177, v0, v142
	v_or_b32_e32 v142, 27, v171
	v_min_u32_e32 v143, v142, v193
	v_max_u32_e32 v142, v142, v193
	v_cvt_f32_u32_e32 v146, v146
	v_pk_mul_f32 v[20:21], v[20:21], v[176:177]
	s_nop 0
	v_mfma_f32_32x32x16_bf16 v[2:17], v[138:141], v[66:69], v[2:17]
	v_sub_u32_e32 v138, v142, v143
	v_cvt_f32_u32_e32 v138, v138
	v_mul_f32_e32 v0, v194, v146
	v_cmp_gt_f32_e32 vcc, s34, v0
	v_mul_f32_e32 v139, v194, v138
	s_nop 0
	v_cndmask_b32_e32 v0, 0, v187, vcc
	s_nop 0
	v_mfma_f32_32x32x16_bf16 v[2:17], v[130:133], v[62:65], v[2:17]
	v_cmp_gt_f32_e64 s[0:1], s34, v139
	v_fmac_f32_e32 v0, v194, v146
	v_exp_f32_e32 v0, v0
	v_cndmask_b32_e64 v130, 0, v187, s[0:1]
	v_fmac_f32_e32 v130, v194, v138
	v_exp_f32_e32 v131, v130
	v_cndmask_b32_e32 v130, 0, v188, vcc
	v_ldexp_f32 v130, v0, v130
	v_cndmask_b32_e64 v0, 0, v188, s[0:1]
	v_ldexp_f32 v131, v131, v0
	v_or_b32_e32 v0, 32, v171
	s_nop 0
	v_mfma_f32_32x32x16_bf16 v[2:17], v[126:129], v[58:61], v[2:17]
	v_cvt_pk_bf16_f32 v127, v18, v19
	v_min_u32_e32 v18, v0, v193
	v_max_u32_e32 v0, v0, v193
	v_sub_u32_e32 v0, v0, v18
	v_cvt_f32_u32_e32 v0, v0
	v_or_b32_e32 v19, 33, v171
	v_cvt_pk_bf16_f32 v128, v20, v21
	v_min_u32_e32 v20, v19, v193
	v_max_u32_e32 v19, v19, v193
	v_sub_u32_e32 v19, v19, v20
	v_cvt_f32_u32_e32 v19, v19
	v_mul_f32_e32 v18, v194, v0
	v_cmp_gt_f32_e32 vcc, s34, v18
	s_nop 0
	v_mfma_f32_32x32x16_bf16 v[2:17], v[134:137], v[54:57], v[2:17]
	v_mul_f32_e32 v20, v194, v19
	v_cndmask_b32_e32 v18, 0, v187, vcc
	v_fmac_f32_e32 v18, v194, v0
	v_exp_f32_e32 v0, v18
	v_cndmask_b32_e32 v18, 0, v188, vcc
	v_cmp_gt_f32_e32 vcc, s34, v20
	v_pk_mul_f32 v[22:23], v[22:23], v[130:131]
	v_ldexp_f32 v18, v0, v18
	v_cndmask_b32_e32 v20, 0, v187, vcc
	v_fmac_f32_e32 v20, v194, v19
	v_exp_f32_e32 v19, v20
	v_or_b32_e32 v20, 34, v171
	v_min_u32_e32 v21, v20, v193
	v_max_u32_e32 v20, v20, v193
	v_sub_u32_e32 v20, v20, v21
	v_cvt_f32_u32_e32 v20, v20
	v_cndmask_b32_e32 v0, 0, v188, vcc
	v_ldexp_f32 v19, v19, v0
	s_waitcnt vmcnt(0)
	v_mfma_f32_32x32x16_bf16 v[2:17], v[28:31], v[50:53], v[2:17]
	v_mul_f32_e32 v0, v194, v20
	v_cmp_gt_f32_e32 vcc, s34, v0
	v_cvt_pk_bf16_f32 v129, v22, v23
	v_cvt_pk_bf16_f32 v130, v150, v151
	v_cndmask_b32_e32 v0, 0, v187, vcc
	v_fmac_f32_e32 v0, v194, v20
	v_or_b32_e32 v20, 35, v171
	v_min_u32_e32 v21, v20, v193
	v_max_u32_e32 v20, v20, v193
	v_sub_u32_e32 v20, v20, v21
	v_exp_f32_e32 v0, v0
	v_cvt_f32_u32_e32 v20, v20
	v_pk_mul_f32 v[176:177], v[2:3], v[18:19]
	v_cndmask_b32_e32 v2, 0, v188, vcc
	v_ldexp_f32 v2, v0, v2
	v_mul_f32_e32 v0, v194, v20
	v_cmp_gt_f32_e32 vcc, s34, v0
	v_or_b32_e32 v3, 40, v171
	v_min_u32_e32 v18, v3, v193
	v_cndmask_b32_e32 v0, 0, v187, vcc
	v_fmac_f32_e32 v0, v194, v20
	v_exp_f32_e32 v0, v0
	v_max_u32_e32 v3, v3, v193
	v_sub_u32_e32 v3, v3, v18
	v_cvt_f32_u32_e32 v18, v3
	v_cndmask_b32_e32 v3, 0, v188, vcc
	v_ldexp_f32 v3, v0, v3
	v_pk_mul_f32 v[178:179], v[4:5], v[2:3]
	v_or_b32_e32 v2, 41, v171
	v_min_u32_e32 v3, v2, v193
	v_max_u32_e32 v2, v2, v193
	v_sub_u32_e32 v2, v2, v3
	v_cvt_f32_u32_e32 v2, v2
	v_mul_f32_e32 v0, v194, v18
	v_cmp_gt_f32_e32 vcc, s34, v0
	v_cvt_pk_bf16_f32 v131, v152, v153
	v_mul_f32_e32 v4, v194, v2
	v_cndmask_b32_e32 v0, 0, v187, vcc
	v_cndmask_b32_e32 v3, 0, v188, vcc
	v_cmp_gt_f32_e32 vcc, s34, v4
	v_fmac_f32_e32 v0, v194, v18
	v_exp_f32_e32 v0, v0
	v_cndmask_b32_e32 v4, 0, v187, vcc
	v_fmac_f32_e32 v4, v194, v2
	v_or_b32_e32 v2, 42, v171
	v_min_u32_e32 v5, v2, v193
	v_max_u32_e32 v2, v2, v193
	v_sub_u32_e32 v2, v2, v5
	v_exp_f32_e32 v4, v4
	v_cvt_f32_u32_e32 v5, v2
	v_ldexp_f32 v2, v0, v3
	v_cndmask_b32_e32 v0, 0, v188, vcc
	v_ldexp_f32 v3, v4, v0
	v_mul_f32_e32 v0, v194, v5
	v_cmp_gt_f32_e32 vcc, s34, v0
	v_or_b32_e32 v4, 43, v171
	v_pk_mul_f32 v[6:7], v[6:7], v[2:3]
	v_cndmask_b32_e32 v0, 0, v187, vcc
	v_fmac_f32_e32 v0, v194, v5
	v_min_u32_e32 v5, v4, v193
	v_max_u32_e32 v4, v4, v193
	v_sub_u32_e32 v4, v4, v5
	v_exp_f32_e32 v0, v0
	v_cvt_f32_u32_e32 v4, v4
	v_cndmask_b32_e32 v2, 0, v188, vcc
	v_or_b32_e32 v3, 48, v171
	v_ldexp_f32 v2, v0, v2
	v_mul_f32_e32 v0, v194, v4
	v_cmp_gt_f32_e32 vcc, s34, v0
	v_cvt_pk_bf16_f32 v132, v156, v157
	v_cvt_pk_bf16_f32 v133, v158, v159
	v_cndmask_b32_e32 v0, 0, v187, vcc
	v_fmac_f32_e32 v0, v194, v4
	v_exp_f32_e32 v0, v0
	v_min_u32_e32 v4, v3, v193
	v_max_u32_e32 v3, v3, v193
	v_sub_u32_e32 v3, v3, v4
	v_cvt_f32_u32_e32 v4, v3
	v_cndmask_b32_e32 v3, 0, v188, vcc
	v_ldexp_f32 v3, v0, v3
	v_pk_mul_f32 v[8:9], v[8:9], v[2:3]
	v_or_b32_e32 v2, 49, v171
	v_min_u32_e32 v3, v2, v193
	v_max_u32_e32 v2, v2, v193
	v_sub_u32_e32 v2, v2, v3
	v_cvt_f32_u32_e32 v2, v2
	v_mul_f32_e32 v0, v194, v4
	v_cmp_gt_f32_e32 vcc, s34, v0
	v_cvt_pk_bf16_f32 v126, v160, v161
	s_nop 0
	v_cndmask_b32_e32 v0, 0, v187, vcc
	v_fmac_f32_e32 v0, v194, v4
	v_mul_f32_e32 v4, v194, v2
	v_cndmask_b32_e32 v3, 0, v188, vcc
	v_cmp_gt_f32_e32 vcc, s34, v4
	v_exp_f32_e32 v0, v0
	s_nop 0
	v_cndmask_b32_e32 v4, 0, v187, vcc
	v_fmac_f32_e32 v4, v194, v2
	v_or_b32_e32 v2, 50, v171
	v_min_u32_e32 v5, v2, v193
	v_max_u32_e32 v2, v2, v193
	v_sub_u32_e32 v2, v2, v5
	v_exp_f32_e32 v4, v4
	v_cvt_f32_u32_e32 v5, v2
	v_ldexp_f32 v2, v0, v3
	v_cndmask_b32_e32 v0, 0, v188, vcc
	v_ldexp_f32 v3, v4, v0
	v_mul_f32_e32 v0, v194, v5
	v_cmp_gt_f32_e32 vcc, s34, v0
	v_or_b32_e32 v4, 51, v171
	v_pk_mul_f32 v[10:11], v[10:11], v[2:3]
	v_cndmask_b32_e32 v0, 0, v187, vcc
	v_fmac_f32_e32 v0, v194, v5
	v_exp_f32_e32 v0, v0
	v_min_u32_e32 v5, v4, v193
	v_max_u32_e32 v4, v4, v193
	v_cndmask_b32_e32 v2, 0, v188, vcc
	v_sub_u32_e32 v4, v4, v5
	v_ldexp_f32 v18, v0, v2
	v_or_b32_e32 v2, 56, v171
	v_cvt_f32_u32_e32 v4, v4
	v_min_u32_e32 v3, v2, v193
	v_max_u32_e32 v2, v2, v193
	v_sub_u32_e32 v2, v2, v3
	v_cvt_f32_u32_e32 v22, v2
	v_or_b32_e32 v2, v192, v195
	v_ashrrev_i32_e32 v3, 31, v2
	v_mul_f32_e32 v0, v194, v4
	v_lshlrev_b64 v[2:3], 8, v[2:3]
	v_cmp_gt_f32_e32 vcc, s34, v0
	v_lshl_add_u64 v[2:3], v[154:155], 0, v[2:3]
	v_lshl_add_u64 v[20:21], v[2:3], 0, v[32:33]
	v_cndmask_b32_e32 v0, 0, v187, vcc
	v_fmac_f32_e32 v0, v194, v4
	ds_read_b128 v[2:5], v233 offset:8704
	ds_read_b128 v[158:161], v233 offset:8736
	ds_read_b128 v[154:157], v233 offset:8768
	ds_read_b128 v[150:153], v233 offset:8800
	ds_read_b128 v[146:149], v233 offset:8832
	ds_read_b128 v[142:145], v233 offset:8864
	ds_read_b128 v[138:141], v233 offset:8896
	ds_read_b128 v[134:137], v233 offset:8928
	v_exp_f32_e32 v0, v0
	v_cndmask_b32_e32 v19, 0, v188, vcc
	v_ldexp_f32 v19, v0, v19
	v_mul_f32_e32 v0, v194, v22
	v_cmp_gt_f32_e32 vcc, s34, v0
	v_pk_mul_f32 v[12:13], v[12:13], v[18:19]
	v_or_b32_e32 v18, 57, v171
	v_cndmask_b32_e32 v0, 0, v187, vcc
	v_fmac_f32_e32 v0, v194, v22
	v_exp_f32_e32 v0, v0
	v_min_u32_e32 v19, v18, v193
	v_max_u32_e32 v18, v18, v193
	v_sub_u32_e32 v18, v18, v19
	v_cvt_f32_u32_e32 v195, v18
	v_cndmask_b32_e32 v18, 0, v188, vcc
	v_ldexp_f32 v196, v0, v18
	s_waitcnt lgkmcnt(8)
	v_mfma_f32_32x32x16_bf16 v[18:33], v[24:27], v[78:81], 0
	v_mul_f32_e32 v0, v194, v195
	v_cmp_gt_f32_e32 vcc, s34, v0
	s_nop 1
	v_cndmask_b32_e32 v0, 0, v187, vcc
	v_fmac_f32_e32 v0, v194, v195
	v_or_b32_e32 v195, 58, v171
	s_nop 0
	v_mfma_f32_32x32x16_bf16 v[18:33], v[122:125], v[74:77], v[18:33]
	v_min_u32_e32 v197, v195, v193
	v_max_u32_e32 v122, v195, v193
	v_sub_u32_e32 v122, v122, v197
	v_exp_f32_e32 v0, v0
	v_cvt_f32_u32_e32 v122, v122
	v_cndmask_b32_e32 v123, 0, v188, vcc
	v_ldexp_f32 v197, v0, v123
	s_nop 0
	v_mfma_f32_32x32x16_bf16 v[18:33], v[118:121], v[70:73], v[18:33]
	v_or_b32_e32 v118, 59, v171
	v_min_u32_e32 v119, v118, v193
	v_max_u32_e32 v118, v118, v193
	v_sub_u32_e32 v118, v118, v119
	v_cvt_f32_u32_e32 v118, v118
	v_mul_f32_e32 v0, v194, v122
	v_cmp_gt_f32_e32 vcc, s34, v0
	s_nop 0
	v_mfma_f32_32x32x16_bf16 v[18:33], v[114:117], v[66:69], v[18:33]
	v_mul_f32_e32 v114, v194, v118
	v_cndmask_b32_e32 v0, 0, v187, vcc
	v_cmp_gt_f32_e64 s[0:1], s34, v114
	v_fmac_f32_e32 v0, v194, v122
	v_exp_f32_e32 v0, v0
	v_cndmask_b32_e64 v114, 0, v187, s[0:1]
	v_fmac_f32_e32 v114, v194, v118
	s_nop 0
	v_mfma_f32_32x32x16_bf16 v[18:33], v[110:113], v[62:65], v[18:33]
	v_exp_f32_e32 v114, v114
	v_cndmask_b32_e32 v110, 0, v188, vcc
	v_ldexp_f32 v110, v0, v110
	v_cndmask_b32_e64 v0, 0, v188, s[0:1]
	v_ldexp_f32 v111, v114, v0
	v_add_u32_e32 v0, 1, v193
	v_cvt_f32_u32_e32 v0, v0
	s_nop 0
	v_mfma_f32_32x32x16_bf16 v[18:33], v[46:49], v[58:61], v[18:33]
	v_cvt_pk_bf16_f32 v116, v6, v7
	v_mul_f32_e64 v14, v14, v196
	v_mul_f32_e64 v15, v15, v197
	v_mul_f32_e32 v6, v194, v0
	v_cmp_gt_f32_e32 vcc, s34, v6
	v_pk_mul_f32 v[16:17], v[16:17], v[110:111]
	v_cvt_pk_bf16_f32 v114, v176, v177
	v_cndmask_b32_e32 v6, 0, v187, vcc
	s_nop 0
	v_mfma_f32_32x32x16_bf16 v[18:33], v[42:45], v[54:57], v[18:33]
	v_fmac_f32_e32 v6, v194, v0
	v_exp_f32_e32 v0, v6
	v_cndmask_b32_e32 v6, 0, v188, vcc
	v_cvt_pk_bf16_f32 v115, v178, v179
	v_cvt_pk_bf16_f32 v117, v8, v9
	v_ldexp_f32 v0, v0, v6
	v_cvt_pk_bf16_f32 v110, v10, v11
	s_nop 0
	v_mfma_f32_32x32x16_bf16 v[18:33], v[38:41], v[50:53], v[18:33]
	v_cvt_pk_bf16_f32 v111, v12, v13
	v_cvt_pk_bf16_f32 v112, v14, v15
	v_cvt_pk_bf16_f32 v113, v16, v17
	s_waitcnt lgkmcnt(7)
	v_mfma_f32_32x32x16_bf16 v[2:17], v[2:5], v[78:81], 0
	s_movk_i32 s0, 0xffe0
	v_cmp_eq_u32_e32 vcc, 0, v173
	s_barrier
	s_waitcnt lgkmcnt(6)
	v_mfma_f32_32x32x16_bf16 v[2:17], v[158:161], v[74:77], v[2:17]
	s_waitcnt lgkmcnt(5)
	v_mfma_f32_32x32x16_bf16 v[2:17], v[154:157], v[70:73], v[2:17]
	s_waitcnt lgkmcnt(4)
	v_mfma_f32_32x32x16_bf16 v[2:17], v[150:153], v[66:69], v[2:17]
	s_waitcnt lgkmcnt(3)
	v_mfma_f32_32x32x16_bf16 v[2:17], v[146:149], v[62:65], v[2:17]
	s_waitcnt lgkmcnt(2)
	v_mfma_f32_32x32x16_bf16 v[2:17], v[142:145], v[58:61], v[2:17]
	s_waitcnt lgkmcnt(1)
	v_mfma_f32_32x32x16_bf16 v[2:17], v[138:141], v[54:57], v[2:17]
	v_mfma_f32_32x32x16_bf16 v[34:49], v[34:37], v[130:133], 0
	s_waitcnt lgkmcnt(0)
	v_mfma_f32_32x32x16_bf16 v[2:17], v[134:137], v[50:53], v[2:17]
	v_mfma_f32_32x32x16_bf16 v[50:65], v[94:97], v[130:133], 0
	v_mfma_f32_32x32x16_bf16 v[34:49], v[106:109], v[126:129], v[34:49]
	v_mfma_f32_32x32x16_bf16 v[50:65], v[90:93], v[126:129], v[50:65]
	v_mfma_f32_32x32x16_bf16 v[34:49], v[102:105], v[114:117], v[34:49]
	v_mfma_f32_32x32x16_bf16 v[50:65], v[86:89], v[114:117], v[50:65]
	v_mfma_f32_32x32x16_bf16 v[34:49], v[98:101], v[110:113], v[34:49]
	v_mfma_f32_32x32x16_bf16 v[50:65], v[82:85], v[110:113], v[50:65]
	s_nop 10
	v_fma_f32 v66, v0, v18, v34
	v_fma_f32 v67, v0, v19, v35
	v_fma_f32 v68, v0, v20, v36
	v_fma_f32 v69, v0, v21, v37
	v_fma_f32 v70, v0, v22, v38
	v_fma_f32 v71, v0, v23, v39
	v_pk_fma_f32 v[38:39], v[0:1], v[24:25], v[40:41] op_sel_hi:[0,1,1]
	v_pk_fma_f32 v[24:25], v[0:1], v[30:31], v[46:47] op_sel_hi:[0,1,1]
	v_pk_mul_f32 v[30:31], v[66:67], v[66:67]
	v_pk_fma_f32 v[36:37], v[0:1], v[26:27], v[42:43] op_sel_hi:[0,1,1]
	v_pk_fma_f32 v[34:35], v[0:1], v[28:29], v[44:45] op_sel_hi:[0,1,1]
	v_pk_fma_f32 v[22:23], v[0:1], v[32:33], v[48:49] op_sel_hi:[0,1,1]
	v_pk_mul_f32 v[32:33], v[68:69], v[68:69]
	v_pk_fma_f32 v[28:29], v[0:1], v[2:3], v[50:51] op_sel_hi:[0,1,1]
	v_pk_fma_f32 v[26:27], v[0:1], v[4:5], v[52:53] op_sel_hi:[0,1,1]
	v_pk_fma_f32 v[20:21], v[0:1], v[6:7], v[54:55] op_sel_hi:[0,1,1]
	v_pk_fma_f32 v[18:19], v[0:1], v[8:9], v[56:57] op_sel_hi:[0,1,1]
	v_pk_fma_f32 v[8:9], v[0:1], v[10:11], v[58:59] op_sel_hi:[0,1,1]
	v_pk_fma_f32 v[6:7], v[0:1], v[12:13], v[60:61] op_sel_hi:[0,1,1]
	v_pk_fma_f32 v[4:5], v[0:1], v[14:15], v[62:63] op_sel_hi:[0,1,1]
	v_pk_fma_f32 v[2:3], v[0:1], v[16:17], v[64:65] op_sel_hi:[0,1,1]
	v_add_f32_e32 v0, v30, v31
	v_add_f32_e32 v0, v32, v0
	v_pk_mul_f32 v[40:41], v[70:71], v[70:71]
	v_add_f32_e32 v0, v33, v0
	v_add_f32_e32 v0, v40, v0
	v_pk_mul_f32 v[42:43], v[38:39], v[38:39]
	v_add_f32_e32 v0, v41, v0
	v_add_f32_e32 v0, v42, v0
	v_pk_mul_f32 v[44:45], v[36:37], v[36:37]
	v_add_f32_e32 v0, v43, v0
	v_add_f32_e32 v0, v44, v0
	v_pk_mul_f32 v[46:47], v[34:35], v[34:35]
	v_add_f32_e32 v0, v45, v0
	v_add_f32_e32 v0, v46, v0
	v_pk_mul_f32 v[48:49], v[24:25], v[24:25]
	v_add_f32_e32 v0, v47, v0
	v_add_f32_e32 v0, v48, v0
	v_pk_mul_f32 v[72:73], v[22:23], v[22:23]
	v_add_f32_e32 v0, v49, v0
	v_add_f32_e32 v0, v72, v0
	v_pk_mul_f32 v[50:51], v[28:29], v[28:29]
	v_add_f32_e32 v0, v73, v0
	v_add_f32_e32 v0, v50, v0
	v_pk_mul_f32 v[52:53], v[26:27], v[26:27]
	v_add_f32_e32 v0, v51, v0
	v_add_f32_e32 v0, v52, v0
	v_pk_mul_f32 v[54:55], v[20:21], v[20:21]
	v_add_f32_e32 v0, v53, v0
	v_add_f32_e32 v0, v54, v0
	v_pk_mul_f32 v[56:57], v[18:19], v[18:19]
	v_add_f32_e32 v0, v55, v0
	v_add_f32_e32 v0, v56, v0
	v_pk_mul_f32 v[10:11], v[8:9], v[8:9]
	v_add_f32_e32 v0, v57, v0
	v_add_f32_e32 v0, v10, v0
	v_pk_mul_f32 v[12:13], v[6:7], v[6:7]
	v_add_f32_e32 v0, v11, v0
	v_add_f32_e32 v0, v12, v0
	v_pk_mul_f32 v[14:15], v[4:5], v[4:5]
	v_add_f32_e32 v0, v13, v0
	v_add_f32_e32 v0, v14, v0
	v_pk_mul_f32 v[16:17], v[2:3], v[2:3]
	v_add_f32_e32 v0, v15, v0
	v_add_f32_e32 v0, v16, v0
	v_add_f32_e32 v0, v17, v0
	ds_bpermute_b32 v12, v234, v0
	v_bfi_b32 v10, s0, v191, v172
	v_lshl_add_u32 v11, v10, 2, v182
	s_and_saveexec_b64 s[0:1], vcc
	s_cbranch_execz .LBB0_871
	s_waitcnt lgkmcnt(0)
	v_add_f32_e32 v0, v0, v12
	ds_write_b32 v11, v0
	s_branch .LBB0_871
